# r55 layout variant: final-norm phase code (after out-proj epilogue) shifted by 4 bytes (code alignment tuning)
# speedup vs baseline: 1.0023x; 1.0006x over previous
.LBB0_1319:
	global_load_dword v21, v0, s[8:9] sc1
	s_mov_b64 s[12:13], -1
	s_waitcnt vmcnt(0)
	v_readfirstlane_b32 s7, v21
	s_cmp_gt_u32 s7, 31
	s_cbranch_scc1 .LBB0_1318
	s_mov_b64 s[12:13], 0
	s_sleep 2
	s_branch .LBB0_1318
	s_nop 0
